# up epilogue H stores with cache policy 'sc0' (policy sweep), on top of v59
# baseline (speedup 1.0000x reference)
; __device__ __forceinline__ unsigned cvt_pk_bf16(float lo, float hi) { unsigned r; asm volatile("v_cvt_pk_bf16_f32 %0, %1, %2" : "=v"(r) : "v"(lo), "v"(hi)); return r; }
;     __device__ __forceinline__ void operator()(const f32x4 (&acc)[2][2][4][2], const Unit& u, int ui, int wr, int wc, int fr, int fq) const {
;     ...
;             for (int m = 0; m < 4; ++m) rs[ai][m] = row_rstd(lds, ui, ai * HALF + wr * 64 + m * 16 + fr);
; #pragma unroll
;         for (int ai = 0; ai < 2; ++ai)
; #pragma unroll
;             for (int m = 0; m < 4; ++m) { const float r = rs[ai][m]; const int row = row0 + ai * HALF + m * 16;
;                 const float c1 = r * -1.44269504089f, r2 = r * r; u32x4 w;
; #pragma unroll
;                 for (int n = 0; n < 2; ++n)
; #pragma unroll
;                     for (int p = 0; p < 2; ++p) { const f32x2 g = (f32x2){acc[ai][0][m][n][2 * p], acc[ai][0][m][n][2 * p + 1]}, uu = (f32x2){acc[ai][1][m][n][2 * p], acc[ai][1][m][n][2 * p + 1]};
;                         const f32x2 t = g * c1; f32x2 d; d.x = __builtin_amdgcn_exp2f(t.x); d.y = __builtin_amdgcn_exp2f(t.y); d = d + 1.0f;
;                         f32x2 q; q.x = __builtin_amdgcn_rcpf(d.x); q.y = __builtin_amdgcn_rcpf(d.y);
;                         const f32x2 hh = (g * uu) * (q * r2); w[2 * n + p] = cvt_pk_bf16(hh.x, hh.y); }
;                 __builtin_nontemporal_store(w, (u32x4*)(H + (size_t)row * ldh + col0)); }
.LBB0_449:
	v_mov_b32_e32 v140, v147
	v_mov_b32_e32 v167, v164
	v_pk_mul_f32 v[120:121], v[124:125], v[120:121]
	v_add_u32_e32 v171, s35, v140
	v_lshlrev_b32_e32 v140, 2, v171
	v_lshl_add_u32 v140, s48, 10, v140
	v_add_u32_e32 v140, 0x20400, v140
	ds_read2_b32 v[168:169], v140 offset1:16
	ds_read2_b32 v[162:163], v140 offset0:32 offset1:48
	ds_read2_b32 v[142:143], v140 offset0:128 offset1:144
	ds_read2_b32 v[140:141], v140 offset0:160 offset1:176
	v_pk_mul_f32 v[122:123], v[126:127], v[122:123]
	s_waitcnt lgkmcnt(0)
	v_mul_f32_e32 v172, 0xbfb8aa3b, v168
	v_pk_mul_f32 v[174:175], v[124:125], v[172:173] op_sel_hi:[1,0]
	v_pk_mul_f32 v[124:125], v[126:127], v[172:173] op_sel_hi:[1,0]
	v_exp_f32_e32 v174, v174
	v_exp_f32_e32 v175, v175
	v_exp_f32_e32 v124, v124
	v_exp_f32_e32 v125, v125
	v_mul_f32_e32 v168, v168, v168
	v_pk_add_f32 v[174:175], v[174:175], 1.0 op_sel_hi:[1,0]
	v_pk_mul_f32 v[112:113], v[116:117], v[112:113]
	v_rcp_f32_e32 v174, v174
	v_rcp_f32_e32 v175, v175
	v_pk_add_f32 v[124:125], v[124:125], 1.0 op_sel_hi:[1,0]
	v_pk_mul_f32 v[114:115], v[118:119], v[114:115]
	v_rcp_f32_e32 v124, v124
	v_rcp_f32_e32 v125, v125
	v_pk_mul_f32 v[126:127], v[168:169], v[174:175] op_sel_hi:[0,1]
	v_pk_mul_f32 v[120:121], v[120:121], v[126:127]
	v_pk_mul_f32 v[126:127], v[116:117], v[172:173] op_sel_hi:[1,0]
	v_pk_mul_f32 v[124:125], v[168:169], v[124:125] op_sel_hi:[0,1]
	v_exp_f32_e32 v126, v126
	v_exp_f32_e32 v127, v127
	v_pk_mul_f32 v[122:123], v[122:123], v[124:125]
	v_pk_mul_f32 v[124:125], v[118:119], v[172:173] op_sel_hi:[1,0]
	v_cvt_pk_bf16_f32 v120, v120, v121
	v_cvt_pk_bf16_f32 v121, v122, v123
	v_pk_add_f32 v[122:123], v[126:127], 1.0 op_sel_hi:[1,0]
	v_exp_f32_e32 v124, v124
	v_exp_f32_e32 v125, v125
	v_rcp_f32_e32 v122, v122
	v_rcp_f32_e32 v123, v123
	s_lshl_b32 s5, s47, 7
	v_pk_add_f32 v[116:117], v[124:125], 1.0 op_sel_hi:[1,0]
	s_or_b32 s5, s5, s36
	v_rcp_f32_e32 v116, v116
	v_rcp_f32_e32 v117, v117
	v_pk_mul_f32 v[118:119], v[168:169], v[122:123] op_sel_hi:[0,1]
	v_pk_mul_f32 v[112:113], v[112:113], v[118:119]
	v_mul_f32_e32 v118, 0xbfb8aa3b, v169
	v_cvt_pk_bf16_f32 v122, v112, v113
	v_pk_mul_f32 v[112:113], v[168:169], v[116:117] op_sel_hi:[0,1]
	v_pk_mul_f32 v[124:125], v[108:109], v[118:119] op_sel_hi:[1,0]
	v_lshl_add_u32 v170, v167, 3, s5
	v_pk_mul_f32 v[112:113], v[114:115], v[112:113]
	v_exp_f32_e32 v124, v124
	v_exp_f32_e32 v125, v125
	v_lshl_add_u32 v167, s46, 8, v171
	v_ashrrev_i32_e32 v171, 31, v170
	v_cvt_pk_bf16_f32 v123, v112, v113
	v_mov_b64_e32 v[112:113], s[20:21]
	v_pk_mul_f32 v[104:105], v[108:109], v[104:105]
	v_pk_mul_f32 v[108:109], v[110:111], v[118:119] op_sel_hi:[1,0]
	v_mad_i64_i32 v[116:117], s[14:15], v167, s59, v[112:113]
	v_lshlrev_b64 v[114:115], 1, v[170:171]
	v_exp_f32_e32 v108, v108
	v_exp_f32_e32 v109, v109
	v_lshl_add_u64 v[116:117], v[116:117], 0, v[114:115]
	global_store_dwordx4 v[116:117], v[120:123], off sc0
	v_mul_f32_e32 v116, v169, v169
	v_pk_add_f32 v[108:109], v[108:109], 1.0 op_sel_hi:[1,0]
	v_pk_add_f32 v[120:121], v[124:125], 1.0 op_sel_hi:[1,0]
	v_rcp_f32_e32 v108, v108
	v_rcp_f32_e32 v120, v120
	v_rcp_f32_e32 v121, v121
	v_rcp_f32_e32 v109, v109
	v_pk_mul_f32 v[106:107], v[110:111], v[106:107]
	v_pk_mul_f32 v[96:97], v[100:101], v[96:97]
	v_pk_mul_f32 v[110:111], v[116:117], v[120:121] op_sel_hi:[0,1]
	v_pk_mul_f32 v[104:105], v[104:105], v[110:111]
	v_pk_mul_f32 v[110:111], v[100:101], v[118:119] op_sel_hi:[1,0]
	v_pk_mul_f32 v[108:109], v[116:117], v[108:109] op_sel_hi:[0,1]
	v_exp_f32_e32 v110, v110
	v_exp_f32_e32 v111, v111
	v_pk_mul_f32 v[106:107], v[106:107], v[108:109]
	v_pk_mul_f32 v[108:109], v[102:103], v[118:119] op_sel_hi:[1,0]
	v_cvt_pk_bf16_f32 v104, v104, v105
	v_cvt_pk_bf16_f32 v105, v106, v107
	v_pk_add_f32 v[106:107], v[110:111], 1.0 op_sel_hi:[1,0]
	v_exp_f32_e32 v108, v108
	v_exp_f32_e32 v109, v109
	v_rcp_f32_e32 v106, v106
	v_rcp_f32_e32 v107, v107
	v_pk_mul_f32 v[98:99], v[102:103], v[98:99]
	v_pk_add_f32 v[100:101], v[108:109], 1.0 op_sel_hi:[1,0]
	v_pk_mul_f32 v[88:89], v[92:93], v[88:89]
	v_rcp_f32_e32 v100, v100
	v_rcp_f32_e32 v101, v101
	v_pk_mul_f32 v[102:103], v[116:117], v[106:107] op_sel_hi:[0,1]
	v_pk_mul_f32 v[96:97], v[96:97], v[102:103]
	v_pk_mul_f32 v[90:91], v[94:95], v[90:91]
	v_cvt_pk_bf16_f32 v106, v96, v97
	v_pk_mul_f32 v[96:97], v[116:117], v[100:101] op_sel_hi:[0,1]
	v_pk_mul_f32 v[96:97], v[98:99], v[96:97]
	v_mul_f32_e32 v98, 0xbfb8aa3b, v162
	v_pk_mul_f32 v[100:101], v[92:93], v[98:99] op_sel_hi:[1,0]
	v_pk_mul_f32 v[92:93], v[94:95], v[98:99] op_sel_hi:[1,0]
	v_exp_f32_e32 v100, v100
	v_exp_f32_e32 v101, v101
	v_exp_f32_e32 v92, v92
	v_exp_f32_e32 v93, v93
	v_cvt_pk_bf16_f32 v107, v96, v97
	v_pk_add_f32 v[100:101], v[100:101], 1.0 op_sel_hi:[1,0]
	v_add_u32_e32 v96, 16, v167
	v_rcp_f32_e32 v100, v100
	v_rcp_f32_e32 v101, v101
	v_mad_i64_i32 v[96:97], s[14:15], v96, s59, v[112:113]
	v_pk_add_f32 v[92:93], v[92:93], 1.0 op_sel_hi:[1,0]
	v_lshl_add_u64 v[96:97], v[96:97], 0, v[114:115]
	v_rcp_f32_e32 v92, v92
	v_rcp_f32_e32 v93, v93
	global_store_dwordx4 v[96:97], v[104:107], off sc0
	v_mul_f32_e32 v96, v162, v162
	v_pk_mul_f32 v[94:95], v[96:97], v[100:101] op_sel_hi:[0,1]
	v_pk_mul_f32 v[88:89], v[88:89], v[94:95]
	v_pk_mul_f32 v[94:95], v[84:85], v[98:99] op_sel_hi:[1,0]
	v_pk_mul_f32 v[92:93], v[96:97], v[92:93] op_sel_hi:[0,1]
	v_exp_f32_e32 v94, v94
	v_exp_f32_e32 v95, v95
	v_pk_mul_f32 v[90:91], v[90:91], v[92:93]
	v_pk_mul_f32 v[92:93], v[86:87], v[98:99] op_sel_hi:[1,0]
	v_cvt_pk_bf16_f32 v88, v88, v89
	v_cvt_pk_bf16_f32 v89, v90, v91
	v_pk_add_f32 v[90:91], v[94:95], 1.0 op_sel_hi:[1,0]
	v_exp_f32_e32 v92, v92
; __device__ __forceinline__ unsigned cvt_pk_bf16(float lo, float hi) { unsigned r; asm volatile("v_cvt_pk_bf16_f32 %0, %1, %2" : "=v"(r) : "v"(lo), "v"(hi)); return r; }
;     __device__ __forceinline__ void operator()(const f32x4 (&acc)[2][2][4][2], const Unit& u, int ui, int wr, int wc, int fr, int fq) const {
;     ...
;             for (int m = 0; m < 4; ++m) { const float r = rs[ai][m]; const int row = row0 + ai * HALF + m * 16;
;                 const float c1 = r * -1.44269504089f, r2 = r * r; u32x4 w;
; #pragma unroll
;                 for (int n = 0; n < 2; ++n)
; #pragma unroll
;                     for (int p = 0; p < 2; ++p) { const f32x2 g = (f32x2){acc[ai][0][m][n][2 * p], acc[ai][0][m][n][2 * p + 1]}, uu = (f32x2){acc[ai][1][m][n][2 * p], acc[ai][1][m][n][2 * p + 1]};
;                         const f32x2 t = g * c1; f32x2 d; d.x = __builtin_amdgcn_exp2f(t.x); d.y = __builtin_amdgcn_exp2f(t.y); d = d + 1.0f;
;                         f32x2 q; q.x = __builtin_amdgcn_rcpf(d.x); q.y = __builtin_amdgcn_rcpf(d.y);
;                         const f32x2 hh = (g * uu) * (q * r2); w[2 * n + p] = cvt_pk_bf16(hh.x, hh.y); }
;                 __builtin_nontemporal_store(w, (u32x4*)(H + (size_t)row * ldh + col0)); }
	v_exp_f32_e32 v93, v93
	v_rcp_f32_e32 v90, v90
	v_rcp_f32_e32 v91, v91
	v_pk_mul_f32 v[80:81], v[84:85], v[80:81]
	v_pk_add_f32 v[84:85], v[92:93], 1.0 op_sel_hi:[1,0]
	v_pk_mul_f32 v[82:83], v[86:87], v[82:83]
	v_rcp_f32_e32 v84, v84
	v_rcp_f32_e32 v85, v85
	v_pk_mul_f32 v[86:87], v[96:97], v[90:91] op_sel_hi:[0,1]
	v_pk_mul_f32 v[80:81], v[80:81], v[86:87]
	v_pk_mul_f32 v[72:73], v[76:77], v[72:73]
	v_cvt_pk_bf16_f32 v90, v80, v81
	v_pk_mul_f32 v[80:81], v[96:97], v[84:85] op_sel_hi:[0,1]
	v_pk_mul_f32 v[80:81], v[82:83], v[80:81]
	v_mul_f32_e32 v82, 0xbfb8aa3b, v163
	v_pk_mul_f32 v[84:85], v[76:77], v[82:83] op_sel_hi:[1,0]
	v_pk_mul_f32 v[76:77], v[78:79], v[82:83] op_sel_hi:[1,0]
	v_exp_f32_e32 v84, v84
	v_exp_f32_e32 v85, v85
	v_exp_f32_e32 v76, v76
	v_exp_f32_e32 v77, v77
	v_cvt_pk_bf16_f32 v91, v80, v81
	v_pk_add_f32 v[84:85], v[84:85], 1.0 op_sel_hi:[1,0]
	v_add_u32_e32 v80, 32, v167
	v_rcp_f32_e32 v84, v84
	v_rcp_f32_e32 v85, v85
	v_mad_i64_i32 v[80:81], s[14:15], v80, s59, v[112:113]
	v_pk_add_f32 v[76:77], v[76:77], 1.0 op_sel_hi:[1,0]
	v_lshl_add_u64 v[80:81], v[80:81], 0, v[114:115]
	v_rcp_f32_e32 v76, v76
	v_rcp_f32_e32 v77, v77
	global_store_dwordx4 v[80:81], v[88:91], off sc0
	v_mul_f32_e32 v80, v163, v163
	v_pk_mul_f32 v[74:75], v[78:79], v[74:75]
	v_pk_mul_f32 v[78:79], v[80:81], v[84:85] op_sel_hi:[0,1]
	v_pk_mul_f32 v[72:73], v[72:73], v[78:79]
	v_pk_mul_f32 v[78:79], v[68:69], v[82:83] op_sel_hi:[1,0]
	v_pk_mul_f32 v[76:77], v[80:81], v[76:77] op_sel_hi:[0,1]
	v_exp_f32_e32 v78, v78
	v_exp_f32_e32 v79, v79
	v_pk_mul_f32 v[74:75], v[74:75], v[76:77]
	v_pk_mul_f32 v[76:77], v[70:71], v[82:83] op_sel_hi:[1,0]
	v_cvt_pk_bf16_f32 v72, v72, v73
	v_cvt_pk_bf16_f32 v73, v74, v75
	v_pk_add_f32 v[74:75], v[78:79], 1.0 op_sel_hi:[1,0]
	v_exp_f32_e32 v76, v76
	v_exp_f32_e32 v77, v77
	v_rcp_f32_e32 v74, v74
	v_rcp_f32_e32 v75, v75
	v_pk_mul_f32 v[64:65], v[68:69], v[64:65]
	v_pk_add_f32 v[68:69], v[76:77], 1.0 op_sel_hi:[1,0]
	v_pk_mul_f32 v[66:67], v[70:71], v[66:67]
	v_rcp_f32_e32 v68, v68
	v_rcp_f32_e32 v69, v69
	v_pk_mul_f32 v[70:71], v[80:81], v[74:75] op_sel_hi:[0,1]
	v_pk_mul_f32 v[64:65], v[64:65], v[70:71]
	v_pk_mul_f32 v[56:57], v[60:61], v[56:57]
	v_cvt_pk_bf16_f32 v74, v64, v65
	v_pk_mul_f32 v[64:65], v[80:81], v[68:69] op_sel_hi:[0,1]
	v_pk_mul_f32 v[64:65], v[66:67], v[64:65]
	v_mul_f32_e32 v66, 0xbfb8aa3b, v142
	v_pk_mul_f32 v[68:69], v[60:61], v[66:67] op_sel_hi:[1,0]
	v_pk_mul_f32 v[60:61], v[62:63], v[66:67] op_sel_hi:[1,0]
	v_exp_f32_e32 v68, v68
	v_exp_f32_e32 v69, v69
	v_exp_f32_e32 v60, v60
	v_exp_f32_e32 v61, v61
	v_cvt_pk_bf16_f32 v75, v64, v65
	v_pk_add_f32 v[68:69], v[68:69], 1.0 op_sel_hi:[1,0]
	v_add_u32_e32 v64, 48, v167
	v_rcp_f32_e32 v68, v68
	v_rcp_f32_e32 v69, v69
	v_mad_i64_i32 v[64:65], s[14:15], v64, s59, v[112:113]
	v_pk_add_f32 v[60:61], v[60:61], 1.0 op_sel_hi:[1,0]
	v_lshl_add_u64 v[64:65], v[64:65], 0, v[114:115]
	v_rcp_f32_e32 v60, v60
	v_rcp_f32_e32 v61, v61
	global_store_dwordx4 v[64:65], v[72:75], off sc0
	v_add_u32_e32 v65, 0x80, v167
	v_mul_f32_e32 v64, v142, v142
	v_pk_mul_f32 v[58:59], v[62:63], v[58:59]
	v_pk_mul_f32 v[62:63], v[64:65], v[68:69] op_sel_hi:[0,1]
	v_pk_mul_f32 v[56:57], v[56:57], v[62:63]
	v_pk_mul_f32 v[62:63], v[52:53], v[66:67] op_sel_hi:[1,0]
	v_pk_mul_f32 v[60:61], v[64:65], v[60:61] op_sel_hi:[0,1]
	v_exp_f32_e32 v62, v62
	v_exp_f32_e32 v63, v63
	v_pk_mul_f32 v[58:59], v[58:59], v[60:61]
	v_pk_mul_f32 v[60:61], v[54:55], v[66:67] op_sel_hi:[1,0]
	v_cvt_pk_bf16_f32 v56, v56, v57
	v_cvt_pk_bf16_f32 v57, v58, v59
	v_pk_add_f32 v[58:59], v[62:63], 1.0 op_sel_hi:[1,0]
	v_exp_f32_e32 v60, v60
	v_exp_f32_e32 v61, v61
	v_rcp_f32_e32 v58, v58
	v_rcp_f32_e32 v59, v59
	v_pk_mul_f32 v[48:49], v[52:53], v[48:49]
	v_pk_add_f32 v[52:53], v[60:61], 1.0 op_sel_hi:[1,0]
	v_pk_mul_f32 v[50:51], v[54:55], v[50:51]
	v_rcp_f32_e32 v52, v52
	v_rcp_f32_e32 v53, v53
	v_pk_mul_f32 v[54:55], v[64:65], v[58:59] op_sel_hi:[0,1]
	v_pk_mul_f32 v[48:49], v[48:49], v[54:55]
	v_pk_mul_f32 v[40:41], v[44:45], v[40:41]
	v_cvt_pk_bf16_f32 v58, v48, v49
	v_pk_mul_f32 v[48:49], v[64:65], v[52:53] op_sel_hi:[0,1]
	v_pk_mul_f32 v[48:49], v[50:51], v[48:49]
	v_mul_f32_e32 v50, 0xbfb8aa3b, v143
	v_pk_mul_f32 v[52:53], v[44:45], v[50:51] op_sel_hi:[1,0]
	v_pk_mul_f32 v[44:45], v[46:47], v[50:51] op_sel_hi:[1,0]
	v_exp_f32_e32 v52, v52
	v_exp_f32_e32 v53, v53
	v_exp_f32_e32 v44, v44
	v_exp_f32_e32 v45, v45
	v_cvt_pk_bf16_f32 v59, v48, v49
	v_pk_add_f32 v[52:53], v[52:53], 1.0 op_sel_hi:[1,0]
	v_mad_i64_i32 v[48:49], s[14:15], v65, s59, v[112:113]
	v_rcp_f32_e32 v52, v52
	v_rcp_f32_e32 v53, v53
	v_pk_add_f32 v[44:45], v[44:45], 1.0 op_sel_hi:[1,0]
	v_lshl_add_u64 v[48:49], v[48:49], 0, v[114:115]
	v_rcp_f32_e32 v44, v44
	v_rcp_f32_e32 v45, v45
	global_store_dwordx4 v[48:49], v[56:59], off sc0
	v_mul_f32_e32 v48, v143, v143
	v_pk_mul_f32 v[42:43], v[46:47], v[42:43]
; __device__ __forceinline__ unsigned cvt_pk_bf16(float lo, float hi) { unsigned r; asm volatile("v_cvt_pk_bf16_f32 %0, %1, %2" : "=v"(r) : "v"(lo), "v"(hi)); return r; }
;     __device__ __forceinline__ void operator()(const f32x4 (&acc)[2][2][4][2], const Unit& u, int ui, int wr, int wc, int fr, int fq) const {
;     ...
;             for (int m = 0; m < 4; ++m) { const float r = rs[ai][m]; const int row = row0 + ai * HALF + m * 16;
;                 const float c1 = r * -1.44269504089f, r2 = r * r; u32x4 w;
; #pragma unroll
;                 for (int n = 0; n < 2; ++n)
; #pragma unroll
;                     for (int p = 0; p < 2; ++p) { const f32x2 g = (f32x2){acc[ai][0][m][n][2 * p], acc[ai][0][m][n][2 * p + 1]}, uu = (f32x2){acc[ai][1][m][n][2 * p], acc[ai][1][m][n][2 * p + 1]};
;                         const f32x2 t = g * c1; f32x2 d; d.x = __builtin_amdgcn_exp2f(t.x); d.y = __builtin_amdgcn_exp2f(t.y); d = d + 1.0f;
;                         f32x2 q; q.x = __builtin_amdgcn_rcpf(d.x); q.y = __builtin_amdgcn_rcpf(d.y);
;                         const f32x2 hh = (g * uu) * (q * r2); w[2 * n + p] = cvt_pk_bf16(hh.x, hh.y); }
;                 __builtin_nontemporal_store(w, (u32x4*)(H + (size_t)row * ldh + col0)); }
	v_pk_mul_f32 v[46:47], v[48:49], v[52:53] op_sel_hi:[0,1]
	v_pk_mul_f32 v[40:41], v[40:41], v[46:47]
	v_pk_mul_f32 v[46:47], v[36:37], v[50:51] op_sel_hi:[1,0]
	v_pk_mul_f32 v[44:45], v[48:49], v[44:45] op_sel_hi:[0,1]
	v_exp_f32_e32 v46, v46
	v_exp_f32_e32 v47, v47
	v_pk_mul_f32 v[42:43], v[42:43], v[44:45]
	v_pk_mul_f32 v[44:45], v[38:39], v[50:51] op_sel_hi:[1,0]
	v_cvt_pk_bf16_f32 v40, v40, v41
	v_cvt_pk_bf16_f32 v41, v42, v43
	v_pk_add_f32 v[42:43], v[46:47], 1.0 op_sel_hi:[1,0]
	v_exp_f32_e32 v44, v44
	v_exp_f32_e32 v45, v45
	v_rcp_f32_e32 v42, v42
	v_rcp_f32_e32 v43, v43
	v_pk_mul_f32 v[32:33], v[36:37], v[32:33]
	v_pk_add_f32 v[36:37], v[44:45], 1.0 op_sel_hi:[1,0]
	v_pk_mul_f32 v[34:35], v[38:39], v[34:35]
	v_rcp_f32_e32 v36, v36
	v_rcp_f32_e32 v37, v37
	v_pk_mul_f32 v[38:39], v[48:49], v[42:43] op_sel_hi:[0,1]
	v_pk_mul_f32 v[32:33], v[32:33], v[38:39]
	v_pk_mul_f32 v[24:25], v[28:29], v[24:25]
	v_cvt_pk_bf16_f32 v42, v32, v33
	v_pk_mul_f32 v[32:33], v[48:49], v[36:37] op_sel_hi:[0,1]
	v_pk_mul_f32 v[32:33], v[34:35], v[32:33]
	v_mul_f32_e32 v34, 0xbfb8aa3b, v140
	v_pk_mul_f32 v[36:37], v[28:29], v[34:35] op_sel_hi:[1,0]
	v_pk_mul_f32 v[28:29], v[30:31], v[34:35] op_sel_hi:[1,0]
	v_exp_f32_e32 v36, v36
	v_exp_f32_e32 v37, v37
	v_exp_f32_e32 v28, v28
	v_exp_f32_e32 v29, v29
	v_cvt_pk_bf16_f32 v43, v32, v33
	v_pk_add_f32 v[36:37], v[36:37], 1.0 op_sel_hi:[1,0]
	v_add_u32_e32 v32, 0x90, v167
	v_rcp_f32_e32 v36, v36
	v_rcp_f32_e32 v37, v37
	v_mad_i64_i32 v[32:33], s[14:15], v32, s59, v[112:113]
	v_pk_add_f32 v[28:29], v[28:29], 1.0 op_sel_hi:[1,0]
	v_lshl_add_u64 v[32:33], v[32:33], 0, v[114:115]
	v_rcp_f32_e32 v28, v28
	v_rcp_f32_e32 v29, v29
	global_store_dwordx4 v[32:33], v[40:43], off sc0
	v_mul_f32_e32 v32, v140, v140
	v_pk_mul_f32 v[26:27], v[30:31], v[26:27]
	v_pk_mul_f32 v[30:31], v[32:33], v[36:37] op_sel_hi:[0,1]
	v_pk_mul_f32 v[24:25], v[24:25], v[30:31]
	v_pk_mul_f32 v[30:31], v[20:21], v[34:35] op_sel_hi:[1,0]
	v_pk_mul_f32 v[28:29], v[32:33], v[28:29] op_sel_hi:[0,1]
	v_exp_f32_e32 v30, v30
	v_exp_f32_e32 v31, v31
	v_pk_mul_f32 v[26:27], v[26:27], v[28:29]
	v_pk_mul_f32 v[28:29], v[22:23], v[34:35] op_sel_hi:[1,0]
	v_cvt_pk_bf16_f32 v24, v24, v25
	v_cvt_pk_bf16_f32 v25, v26, v27
	v_pk_add_f32 v[26:27], v[30:31], 1.0 op_sel_hi:[1,0]
	v_exp_f32_e32 v28, v28
	v_exp_f32_e32 v29, v29
	v_rcp_f32_e32 v26, v26
	v_rcp_f32_e32 v27, v27
	v_pk_mul_f32 v[16:17], v[20:21], v[16:17]
	v_pk_add_f32 v[20:21], v[28:29], 1.0 op_sel_hi:[1,0]
	v_pk_mul_f32 v[18:19], v[22:23], v[18:19]
	v_rcp_f32_e32 v20, v20
	v_rcp_f32_e32 v21, v21
	v_pk_mul_f32 v[22:23], v[32:33], v[26:27] op_sel_hi:[0,1]
	v_pk_mul_f32 v[16:17], v[16:17], v[22:23]
	v_pk_mul_f32 v[8:9], v[12:13], v[8:9]
	v_cvt_pk_bf16_f32 v26, v16, v17
	v_pk_mul_f32 v[16:17], v[32:33], v[20:21] op_sel_hi:[0,1]
	v_pk_mul_f32 v[16:17], v[18:19], v[16:17]
	v_mul_f32_e32 v18, 0xbfb8aa3b, v141
	v_pk_mul_f32 v[20:21], v[12:13], v[18:19] op_sel_hi:[1,0]
	v_pk_mul_f32 v[12:13], v[14:15], v[18:19] op_sel_hi:[1,0]
	v_exp_f32_e32 v20, v20
	v_exp_f32_e32 v21, v21
	v_exp_f32_e32 v12, v12
	v_exp_f32_e32 v13, v13
	v_cvt_pk_bf16_f32 v27, v16, v17
	v_pk_add_f32 v[20:21], v[20:21], 1.0 op_sel_hi:[1,0]
	v_add_u32_e32 v16, 0xa0, v167
	v_rcp_f32_e32 v20, v20
	v_rcp_f32_e32 v21, v21
	v_mad_i64_i32 v[16:17], s[14:15], v16, s59, v[112:113]
	v_pk_add_f32 v[12:13], v[12:13], 1.0 op_sel_hi:[1,0]
	v_lshl_add_u64 v[16:17], v[16:17], 0, v[114:115]
	v_rcp_f32_e32 v12, v12
	v_rcp_f32_e32 v13, v13
	global_store_dwordx4 v[16:17], v[24:27], off sc0
	v_mul_f32_e32 v16, v141, v141
	v_pk_mul_f32 v[10:11], v[14:15], v[10:11]
	v_pk_mul_f32 v[14:15], v[16:17], v[20:21] op_sel_hi:[0,1]
	v_pk_mul_f32 v[8:9], v[8:9], v[14:15]
	v_pk_mul_f32 v[14:15], v[4:5], v[18:19] op_sel_hi:[1,0]
	v_pk_mul_f32 v[12:13], v[16:17], v[12:13] op_sel_hi:[0,1]
	v_exp_f32_e32 v14, v14
	v_exp_f32_e32 v15, v15
	v_pk_mul_f32 v[10:11], v[10:11], v[12:13]
	v_pk_mul_f32 v[12:13], v[6:7], v[18:19] op_sel_hi:[1,0]
	v_cvt_pk_bf16_f32 v8, v8, v9
	v_cvt_pk_bf16_f32 v9, v10, v11
	v_pk_add_f32 v[10:11], v[14:15], 1.0 op_sel_hi:[1,0]
	v_exp_f32_e32 v12, v12
	v_exp_f32_e32 v13, v13
	v_rcp_f32_e32 v10, v10
	v_rcp_f32_e32 v11, v11
	v_pk_mul_f32 v[0:1], v[4:5], v[0:1]
	v_pk_add_f32 v[4:5], v[12:13], 1.0 op_sel_hi:[1,0]
	v_pk_mul_f32 v[2:3], v[6:7], v[2:3]
	v_rcp_f32_e32 v4, v4
	v_rcp_f32_e32 v5, v5
	v_pk_mul_f32 v[6:7], v[16:17], v[10:11] op_sel_hi:[0,1]
	v_pk_mul_f32 v[0:1], v[0:1], v[6:7]
	s_andn2_b64 vcc, exec, s[8:9]
	v_cvt_pk_bf16_f32 v10, v0, v1
	v_pk_mul_f32 v[0:1], v[16:17], v[4:5] op_sel_hi:[0,1]
	v_pk_mul_f32 v[0:1], v[2:3], v[0:1]
	s_mov_b64 s[8:9], -1
	v_cvt_pk_bf16_f32 v11, v0, v1
	v_add_u32_e32 v0, 0xb0, v167
	v_mad_i64_i32 v[0:1], s[14:15], v0, s59, v[112:113]
	v_lshl_add_u64 v[0:1], v[0:1], 0, v[114:115]
	global_store_dwordx4 v[0:1], v[8:11], off sc0
	s_cbranch_vccnz .LBB0_442
	s_andn2_b64 vcc, exec, s[0:1]
	s_cbranch_vccnz .LBB0_441
	s_barrier
	s_branch .LBB0_441
